# attention QK cluster: only 4 K-fragment LDS reads issued before the first MFMA, remaining reads placed in the MFMA gaps (counted lgkmcnt)
# speedup vs baseline: 1.0085x; 1.0043x over previous
; #define MFMA32(a, b, c) __builtin_amdgcn_mfma_f32_32x32x16_bf16((a), (b), (c), 0, 0, 0)
; template <int DK, int DV>
; DI void attn_map(f32x16 (&O)[DV / 32], float& lsum, const u16* qrow, const u16* K1, int ldk1, const u16* K2, int ldk2, const u16* Vt, int nkeys, char* smem) {
;     ...
;     __syncthreads();
; #pragma unroll
;     for (int i = 0; i < NKR; ++i) { int id = tid + i * 256; int row = id / KCH, cc = id - row * KCH; *(u32x4*)(Ks + row * KST + cc * 8) = kreg[i]; }
; #pragma unroll
;     for (int i = 0; i < NVR; ++i) {
;       int id = tid + i * 256; int row = id >> 3, cc = id & 7;
;       u16* base = Vs + row * VST + (cc >> 1) * 16 + (cc & 1) * 4;
;       u32x2 t0 = {vreg[i].x, vreg[i].y}, t1 = {vreg[i].z, vreg[i].w};
;       *(u32x2*)base = t0; *(u32x2*)(base + 8) = t1;
;     }
;     __syncthreads();
;     if (k0 + 64 < nkeys) ATT_LOAD(k0 + 64)
;     f32x16 s[2];
;     __builtin_amdgcn_s_setprio(1);
; #pragma unroll
;     for (int j = 0; j < 2; ++j) {
; #pragma unroll
;       for (int ks = 0; ks < DK / 16; ++ks) {
;         bf16x8 kf = *(const bf16x8*)(Ks + (j * 32 + r) * KST + ks * 16 + 8 * h);
;         s[j] = (ks == 0) ? MFMA32(kf, qf[ks], negm) : MFMA32(kf, qf[ks], s[j]);
;       }
;     }
;     {
;       constexpr int NQK = 2 * (DK / 16);
;       __builtin_amdgcn_sched_group_barrier(0x100, 2, 0);
; #pragma unroll
;       for (int q = 0; q < NQK - 2; ++q) { __builtin_amdgcn_sched_group_barrier(0x008, 1, 0); __builtin_amdgcn_sched_group_barrier(0x100, 1, 0); }
;       __builtin_amdgcn_sched_group_barrier(0x008, 2, 0);
;     }
.LBB0_382:
	s_cmpk_gt_u32 s10, 0x10bf
	s_cselect_b64 s[8:9], -1, 0
	s_and_b64 vcc, exec, s[8:9]
	s_barrier
	s_waitcnt vmcnt(5)
	ds_write_b128 v188, v[144:147]
	s_waitcnt vmcnt(4)
	ds_write_b128 v189, v[148:151]
	s_waitcnt vmcnt(3)
	ds_write2_b64 v190, v[152:153], v[154:155] offset0:128 offset1:130
	s_waitcnt vmcnt(2)
	ds_write2_b64 v191, v[156:157], v[158:159] offset0:128 offset1:130
	s_waitcnt vmcnt(1)
	ds_write2_b64 v192, v[160:161], v[162:163] offset0:128 offset1:130
	s_waitcnt vmcnt(0)
	ds_write2_b64 v193, v[164:165], v[166:167] offset0:128 offset1:130
	s_waitcnt lgkmcnt(0)
	s_barrier
	s_cbranch_vccnz .Lqk_last_A
	s_setprio 1
	ds_read_b128 v[200:203], v168
	ds_read_b128 v[204:207], v168 offset:32
	ds_read_b128 v[208:211], v168 offset:64
	ds_read_b128 v[212:215], v168 offset:96
	s_waitcnt lgkmcnt(3)
	v_mfma_f32_32x32x16_bf16 v[96:111], v[200:203], v[128:131], v[16:31]
	ds_read_b128 v[216:219], v168 offset:4608
	ds_read_b128 v[200:203], v168 offset:9216
	v_lshl_add_u64 v[236:237], v[186:187], 0, s[6:7]
	global_load_dwordx4 v[144:147], v[236:237], off
	s_waitcnt lgkmcnt(4)
	v_mfma_f32_32x32x16_bf16 v[96:111], v[204:207], v[132:135], v[96:111]
	ds_read_b128 v[220:223], v168 offset:4640
	ds_read_b128 v[204:207], v168 offset:13824
	v_lshl_add_u64 v[236:237], v[184:185], 0, s[6:7]
	global_load_dwordx4 v[148:151], v[236:237], off
	s_waitcnt lgkmcnt(5)
	v_mfma_f32_32x32x16_bf16 v[96:111], v[208:211], v[136:139], v[96:111]
	ds_read_b128 v[224:227], v168 offset:4672
	ds_read_b128 v[208:211], v168 offset:18432
	v_lshl_add_u64 v[236:237], v[182:183], 0, s[6:7]
	global_load_dwordx4 v[152:155], v[236:237], off
	s_waitcnt lgkmcnt(6)
	v_mfma_f32_32x32x16_bf16 v[96:111], v[212:215], v[140:143], v[96:111]
	ds_read_b128 v[228:231], v168 offset:4704
	ds_read_b128 v[212:215], v168 offset:23040
	v_lshl_add_u64 v[236:237], v[180:181], 0, s[6:7]
	global_load_dwordx4 v[156:159], v[236:237], off
	s_waitcnt lgkmcnt(7)
	v_mfma_f32_32x32x16_bf16 v[112:127], v[216:219], v[128:131], v[16:31]
	ds_read_b128 v[216:219], v168 offset:9248
	v_lshl_add_u64 v[236:237], v[178:179], 0, s[6:7]
	global_load_dwordx4 v[160:163], v[236:237], off
	s_waitcnt lgkmcnt(6)
	v_mfma_f32_32x32x16_bf16 v[112:127], v[220:223], v[132:135], v[112:127]
	ds_read_b128 v[220:223], v168 offset:13856
	v_lshl_add_u64 v[236:237], v[176:177], 0, s[6:7]
	global_load_dwordx4 v[164:167], v[236:237], off
	s_waitcnt lgkmcnt(5)
	v_mfma_f32_32x32x16_bf16 v[112:127], v[224:227], v[136:139], v[112:127]
	ds_read_b128 v[224:227], v168 offset:18464
	s_waitcnt lgkmcnt(4)
	v_mfma_f32_32x32x16_bf16 v[112:127], v[228:231], v[140:143], v[112:127]
	ds_read_b128 v[228:231], v168 offset:23072
	s_setprio 0

; #define MFMA32(a, b, c) __builtin_amdgcn_mfma_f32_32x32x16_bf16((a), (b), (c), 0, 0, 0)
; template <int DK, int DV>
; DI void attn_map(f32x16 (&O)[DV / 32], float& lsum, const u16* qrow, const u16* K1, int ldk1, const u16* K2, int ldk2, const u16* Vt, int nkeys, char* smem) {
;     ...
;     __builtin_amdgcn_s_setprio(1);
; #pragma unroll
;     for (int j = 0; j < 2; ++j) {
; #pragma unroll
;       for (int ks = 0; ks < DK / 16; ++ks) {
;         bf16x8 kf = *(const bf16x8*)(Ks + (j * 32 + r) * KST + ks * 16 + 8 * h);
;         s[j] = (ks == 0) ? MFMA32(kf, qf[ks], negm) : MFMA32(kf, qf[ks], s[j]);
;       }
;     }
;     {
;       constexpr int NQK = 2 * (DK / 16);
;       __builtin_amdgcn_sched_group_barrier(0x100, 2, 0);
; #pragma unroll
;       for (int q = 0; q < NQK - 2; ++q) { __builtin_amdgcn_sched_group_barrier(0x008, 1, 0); __builtin_amdgcn_sched_group_barrier(0x100, 1, 0); }
;       __builtin_amdgcn_sched_group_barrier(0x008, 2, 0);
;     }
.Lqk_last_A:
	s_setprio 1
	ds_read_b128 v[200:203], v168
	ds_read_b128 v[204:207], v168 offset:32
	ds_read_b128 v[208:211], v168 offset:64
	ds_read_b128 v[212:215], v168 offset:96
	s_waitcnt lgkmcnt(3)
	v_mfma_f32_32x32x16_bf16 v[96:111], v[200:203], v[128:131], v[16:31]
	ds_read_b128 v[216:219], v168 offset:4608
	ds_read_b128 v[200:203], v168 offset:9216
	s_waitcnt lgkmcnt(4)
	v_mfma_f32_32x32x16_bf16 v[96:111], v[204:207], v[132:135], v[96:111]
	ds_read_b128 v[220:223], v168 offset:4640
	ds_read_b128 v[204:207], v168 offset:13824
	s_waitcnt lgkmcnt(5)
	v_mfma_f32_32x32x16_bf16 v[96:111], v[208:211], v[136:139], v[96:111]
	ds_read_b128 v[224:227], v168 offset:4672
	ds_read_b128 v[208:211], v168 offset:18432
	s_waitcnt lgkmcnt(6)
	v_mfma_f32_32x32x16_bf16 v[96:111], v[212:215], v[140:143], v[96:111]
	ds_read_b128 v[228:231], v168 offset:4704
	ds_read_b128 v[212:215], v168 offset:23040
	s_waitcnt lgkmcnt(7)
	v_mfma_f32_32x32x16_bf16 v[112:127], v[216:219], v[128:131], v[16:31]
	ds_read_b128 v[216:219], v168 offset:9248
	s_waitcnt lgkmcnt(6)
	v_mfma_f32_32x32x16_bf16 v[112:127], v[220:223], v[132:135], v[112:127]
	ds_read_b128 v[220:223], v168 offset:13856
	s_waitcnt lgkmcnt(5)
	v_mfma_f32_32x32x16_bf16 v[112:127], v[224:227], v[136:139], v[112:127]
	ds_read_b128 v[224:227], v168 offset:18464
	s_waitcnt lgkmcnt(4)
	v_mfma_f32_32x32x16_bf16 v[112:127], v[228:231], v[140:143], v[112:127]
	ds_read_b128 v[228:231], v168 offset:23072
	s_setprio 0
	s_branch .Lqk_join_A

; #define MFMA32(a, b, c) __builtin_amdgcn_mfma_f32_32x32x16_bf16((a), (b), (c), 0, 0, 0)
; template <int DK, int DV>
; DI void attn_map(f32x16 (&O)[DV / 32], float& lsum, const u16* qrow, const u16* K1, int ldk1, const u16* K2, int ldk2, const u16* Vt, int nkeys, char* smem) {
;     ...
;     __syncthreads();
; #pragma unroll
;     for (int i = 0; i < NKR; ++i) { int id = tid + i * 256; int row = id / KCH, cc = id - row * KCH; *(u32x4*)(Ks + row * KST + cc * 8) = kreg[i]; }
; #pragma unroll
;     for (int i = 0; i < NVR; ++i) {
;       int id = tid + i * 256; int row = id >> 3, cc = id & 7;
;       u16* base = Vs + row * VST + (cc >> 1) * 16 + (cc & 1) * 4;
;       u32x2 t0 = {vreg[i].x, vreg[i].y}, t1 = {vreg[i].z, vreg[i].w};
;       *(u32x2*)base = t0; *(u32x2*)(base + 8) = t1;
;     }
;     __syncthreads();
;     if (k0 + 64 < nkeys) ATT_LOAD(k0 + 64)
;     f32x16 s[2];
;     __builtin_amdgcn_s_setprio(1);
; #pragma unroll
;     for (int j = 0; j < 2; ++j) {
; #pragma unroll
;       for (int ks = 0; ks < DK / 16; ++ks) {
;         bf16x8 kf = *(const bf16x8*)(Ks + (j * 32 + r) * KST + ks * 16 + 8 * h);
;         s[j] = (ks == 0) ? MFMA32(kf, qf[ks], negm) : MFMA32(kf, qf[ks], s[j]);
;       }
;     }
;     {
;       constexpr int NQK = 2 * (DK / 16);
;       __builtin_amdgcn_sched_group_barrier(0x100, 2, 0);
; #pragma unroll
;       for (int q = 0; q < NQK - 2; ++q) { __builtin_amdgcn_sched_group_barrier(0x008, 1, 0); __builtin_amdgcn_sched_group_barrier(0x100, 1, 0); }
;       __builtin_amdgcn_sched_group_barrier(0x008, 2, 0);
;     }
.LBB0_404:
	s_cmpk_gt_u32 s10, 0x10bf
	s_cselect_b64 s[6:7], -1, 0
	s_and_b64 vcc, exec, s[6:7]
	s_barrier
	s_waitcnt vmcnt(5)
	ds_write_b128 v189, v[144:147]
	s_waitcnt vmcnt(4)
	ds_write_b128 v190, v[148:151]
	s_waitcnt vmcnt(3)
	ds_write2_b64 v191, v[152:153], v[154:155] offset0:128 offset1:130
	s_waitcnt vmcnt(2)
	ds_write2_b64 v192, v[156:157], v[158:159] offset0:128 offset1:130
	s_waitcnt vmcnt(1)
	ds_write2_b64 v193, v[160:161], v[162:163] offset0:128 offset1:130
	s_waitcnt vmcnt(0)
	ds_write2_b64 v194, v[164:165], v[166:167] offset0:128 offset1:130
	s_waitcnt lgkmcnt(0)
	s_barrier
	s_cbranch_vccnz .Lqk_last_B
	s_setprio 1
	ds_read_b128 v[200:203], v195
	ds_read_b128 v[204:207], v195 offset:32
	ds_read_b128 v[208:211], v195 offset:64
	ds_read_b128 v[212:215], v195 offset:96
	s_waitcnt lgkmcnt(3)
	v_mfma_f32_32x32x16_bf16 v[96:111], v[200:203], v[128:131], v[80:95]
	ds_read_b128 v[216:219], v195 offset:4608
	ds_read_b128 v[200:203], v195 offset:9216
	v_lshl_add_u64 v[236:237], v[182:183], 0, v[168:169]
	global_load_dwordx4 v[144:147], v[186:187], off
	s_waitcnt lgkmcnt(4)
	v_mfma_f32_32x32x16_bf16 v[96:111], v[204:207], v[132:135], v[96:111]
	ds_read_b128 v[220:223], v195 offset:4640
	ds_read_b128 v[204:207], v195 offset:13824
	global_load_dwordx4 v[148:151], v[184:185], off
	global_load_dwordx4 v[152:155], v[236:237], off
	s_waitcnt lgkmcnt(5)
	v_mfma_f32_32x32x16_bf16 v[96:111], v[208:211], v[136:139], v[96:111]
	ds_read_b128 v[224:227], v195 offset:4672
	ds_read_b128 v[208:211], v195 offset:18432
	v_lshl_add_u64 v[236:237], v[180:181], 0, v[168:169]
	global_load_dwordx4 v[156:159], v[236:237], off
	s_waitcnt lgkmcnt(6)
	v_mfma_f32_32x32x16_bf16 v[96:111], v[212:215], v[140:143], v[96:111]
	ds_read_b128 v[228:231], v195 offset:4704
	ds_read_b128 v[212:215], v195 offset:23040
	v_lshl_add_u64 v[236:237], v[178:179], 0, v[168:169]
	global_load_dwordx4 v[160:163], v[236:237], off
	s_waitcnt lgkmcnt(7)
	v_mfma_f32_32x32x16_bf16 v[112:127], v[216:219], v[128:131], v[80:95]
	ds_read_b128 v[216:219], v195 offset:9248
	v_lshl_add_u64 v[236:237], v[176:177], 0, v[168:169]
	global_load_dwordx4 v[164:167], v[236:237], off
	s_waitcnt lgkmcnt(6)
	v_mfma_f32_32x32x16_bf16 v[112:127], v[220:223], v[132:135], v[112:127]
	ds_read_b128 v[220:223], v195 offset:13856
	s_waitcnt lgkmcnt(5)
	v_mfma_f32_32x32x16_bf16 v[112:127], v[224:227], v[136:139], v[112:127]
	ds_read_b128 v[224:227], v195 offset:18464
	s_waitcnt lgkmcnt(4)
	v_mfma_f32_32x32x16_bf16 v[112:127], v[228:231], v[140:143], v[112:127]
	ds_read_b128 v[228:231], v195 offset:23072
	s_setprio 0

; #define MFMA32(a, b, c) __builtin_amdgcn_mfma_f32_32x32x16_bf16((a), (b), (c), 0, 0, 0)
; template <int DK, int DV>
; DI void attn_map(f32x16 (&O)[DV / 32], float& lsum, const u16* qrow, const u16* K1, int ldk1, const u16* K2, int ldk2, const u16* Vt, int nkeys, char* smem) {
;     ...
;     __builtin_amdgcn_s_setprio(1);
; #pragma unroll
;     for (int j = 0; j < 2; ++j) {
; #pragma unroll
;       for (int ks = 0; ks < DK / 16; ++ks) {
;         bf16x8 kf = *(const bf16x8*)(Ks + (j * 32 + r) * KST + ks * 16 + 8 * h);
;         s[j] = (ks == 0) ? MFMA32(kf, qf[ks], negm) : MFMA32(kf, qf[ks], s[j]);
;       }
;     }
;     {
;       constexpr int NQK = 2 * (DK / 16);
;       __builtin_amdgcn_sched_group_barrier(0x100, 2, 0);
; #pragma unroll
;       for (int q = 0; q < NQK - 2; ++q) { __builtin_amdgcn_sched_group_barrier(0x008, 1, 0); __builtin_amdgcn_sched_group_barrier(0x100, 1, 0); }
;       __builtin_amdgcn_sched_group_barrier(0x008, 2, 0);
;     }
.Lqk_last_B:
	s_setprio 1
	ds_read_b128 v[200:203], v195
	ds_read_b128 v[204:207], v195 offset:32
	ds_read_b128 v[208:211], v195 offset:64
	ds_read_b128 v[212:215], v195 offset:96
	s_waitcnt lgkmcnt(3)
	v_mfma_f32_32x32x16_bf16 v[96:111], v[200:203], v[128:131], v[80:95]
	ds_read_b128 v[216:219], v195 offset:4608
	ds_read_b128 v[200:203], v195 offset:9216
	s_waitcnt lgkmcnt(4)
	v_mfma_f32_32x32x16_bf16 v[96:111], v[204:207], v[132:135], v[96:111]
	ds_read_b128 v[220:223], v195 offset:4640
	ds_read_b128 v[204:207], v195 offset:13824
	s_waitcnt lgkmcnt(5)
	v_mfma_f32_32x32x16_bf16 v[96:111], v[208:211], v[136:139], v[96:111]
	ds_read_b128 v[224:227], v195 offset:4672
	ds_read_b128 v[208:211], v195 offset:18432
	s_waitcnt lgkmcnt(6)
	v_mfma_f32_32x32x16_bf16 v[96:111], v[212:215], v[140:143], v[96:111]
	ds_read_b128 v[228:231], v195 offset:4704
	ds_read_b128 v[212:215], v195 offset:23040
	s_waitcnt lgkmcnt(7)
	v_mfma_f32_32x32x16_bf16 v[112:127], v[216:219], v[128:131], v[80:95]
	ds_read_b128 v[216:219], v195 offset:9248
	s_waitcnt lgkmcnt(6)
	v_mfma_f32_32x32x16_bf16 v[112:127], v[220:223], v[132:135], v[112:127]
	ds_read_b128 v[220:223], v195 offset:13856
	s_waitcnt lgkmcnt(5)
	v_mfma_f32_32x32x16_bf16 v[112:127], v[224:227], v[136:139], v[112:127]
	ds_read_b128 v[224:227], v195 offset:18464
	s_waitcnt lgkmcnt(4)
	v_mfma_f32_32x32x16_bf16 v[112:127], v[228:231], v[140:143], v[112:127]
	ds_read_b128 v[228:231], v195 offset:23072
	s_setprio 0
	s_branch .Lqk_join_B

; #define MFMA32(a, b, c) __builtin_amdgcn_mfma_f32_32x32x16_bf16((a), (b), (c), 0, 0, 0)
; template <int DK, int DV>
; DI void attn_map(f32x16 (&O)[DV / 32], float& lsum, const u16* qrow, const u16* K1, int ldk1, const u16* K2, int ldk2, const u16* Vt, int nkeys, char* smem) {
;     ...
;     __syncthreads();
; #pragma unroll
;     for (int i = 0; i < NKR; ++i) { int id = tid + i * 256; int row = id / KCH, cc = id - row * KCH; *(u32x4*)(Ks + row * KST + cc * 8) = kreg[i]; }
; #pragma unroll
;     for (int i = 0; i < NVR; ++i) {
;       int id = tid + i * 256; int row = id >> 3, cc = id & 7;
;       u16* base = Vs + row * VST + (cc >> 1) * 16 + (cc & 1) * 4;
;       u32x2 t0 = {vreg[i].x, vreg[i].y}, t1 = {vreg[i].z, vreg[i].w};
;       *(u32x2*)base = t0; *(u32x2*)(base + 8) = t1;
;     }
;     __syncthreads();
;     if (k0 + 64 < nkeys) ATT_LOAD(k0 + 64)
;     f32x16 s[2];
;     __builtin_amdgcn_s_setprio(1);
; #pragma unroll
;     for (int j = 0; j < 2; ++j) {
; #pragma unroll
;       for (int ks = 0; ks < DK / 16; ++ks) {
;         bf16x8 kf = *(const bf16x8*)(Ks + (j * 32 + r) * KST + ks * 16 + 8 * h);
;         s[j] = (ks == 0) ? MFMA32(kf, qf[ks], negm) : MFMA32(kf, qf[ks], s[j]);
;       }
;     }
;     {
;       constexpr int NQK = 2 * (DK / 16);
;       __builtin_amdgcn_sched_group_barrier(0x100, 2, 0);
; #pragma unroll
;       for (int q = 0; q < NQK - 2; ++q) { __builtin_amdgcn_sched_group_barrier(0x008, 1, 0); __builtin_amdgcn_sched_group_barrier(0x100, 1, 0); }
;       __builtin_amdgcn_sched_group_barrier(0x008, 2, 0);
;     }
.LBB0_436:
	s_add_u32 s6, s10, 64
	s_addc_u32 s7, s11, 0
	s_cmpk_gt_u32 s6, 0x10bf
	s_cselect_b64 s[8:9], -1, 0
	s_and_b64 vcc, exec, s[8:9]
	s_barrier
	s_waitcnt vmcnt(4)
	ds_write_b128 v149, v[120:123]
	s_waitcnt vmcnt(3)
	ds_write_b128 v164, v[124:127]
	s_waitcnt vmcnt(2)
	ds_write_b128 v165, v[128:131]
	s_waitcnt vmcnt(1)
	ds_write2_b64 v166, v[132:133], v[134:135] offset0:128 offset1:130
	s_waitcnt vmcnt(0)
	ds_write2_b64 v167, v[136:137], v[138:139] offset0:128 offset1:130
	s_waitcnt lgkmcnt(0)
	s_barrier
	s_cbranch_vccnz .Lqk_last_C
	s_setprio 1
	ds_read_b128 v[190:193], v143
	ds_read_b128 v[194:197], v143 offset:32
	ds_read_b128 v[198:201], v143 offset:64
	ds_read_b128 v[202:205], v143 offset:96
	s_waitcnt lgkmcnt(3)
	v_mfma_f32_32x32x16_bf16 v[64:79], v[190:193], v[96:99], v[16:31]
	ds_read_b128 v[206:209], v143 offset:128
	ds_read_b128 v[190:193], v168 offset:13312
	v_lshl_add_u64 v[188:189], v[162:163], 0, s[10:11]
	v_lshlrev_b64 v[188:189], v144, v[188:189]
	s_waitcnt lgkmcnt(4)
	v_mfma_f32_32x32x16_bf16 v[64:79], v[194:197], v[100:103], v[64:79]
	ds_read_b128 v[210:213], v143 offset:160
	ds_read_b128 v[194:197], v168 offset:17920
	v_lshl_add_u64 v[188:189], v[146:147], 0, v[188:189]
	global_load_dwordx4 v[120:123], v[188:189], off
	s_waitcnt lgkmcnt(5)
	v_mfma_f32_32x32x16_bf16 v[64:79], v[198:201], v[104:107], v[64:79]
	ds_read_b128 v[214:217], v143 offset:6656
	ds_read_b128 v[198:201], v168 offset:13344
	v_lshl_add_u64 v[188:189], v[160:161], 0, s[10:11]
	v_lshlrev_b64 v[188:189], v148, v[188:189]
	s_waitcnt lgkmcnt(6)
	v_mfma_f32_32x32x16_bf16 v[64:79], v[202:205], v[108:111], v[64:79]
	ds_read_b128 v[218:221], v143 offset:6688
	ds_read_b128 v[202:205], v168 offset:17952
	v_lshl_add_u64 v[188:189], v[150:151], 0, v[188:189]
	global_load_dwordx4 v[124:127], v[188:189], off
	s_waitcnt lgkmcnt(7)
	v_mfma_f32_32x32x16_bf16 v[64:79], v[206:209], v[112:115], v[64:79]
	ds_read_b128 v[222:225], v143 offset:6720
	ds_read_b128 v[206:209], v168 offset:13376
	v_lshl_add_u64 v[188:189], v[158:159], 0, s[10:11]
	v_lshlrev_b64 v[188:189], v142, v[188:189]
	s_waitcnt lgkmcnt(7)
	v_mfma_f32_32x32x16_bf16 v[64:79], v[210:213], v[116:119], v[64:79]
	ds_read_b128 v[226:229], v143 offset:6752
	ds_read_b128 v[210:213], v168 offset:17984
	v_lshl_add_u64 v[188:189], v[152:153], 0, v[188:189]
	global_load_dwordx4 v[128:131], v[188:189], off
	s_waitcnt lgkmcnt(7)
	v_mfma_f32_32x32x16_bf16 v[80:95], v[214:217], v[96:99], v[16:31]
	ds_read_b128 v[230:233], v143 offset:6784
	ds_read_b128 v[214:217], v168 offset:13408
	global_load_dwordx4 v[132:135], v[156:157], off
	global_load_dwordx4 v[136:139], v[154:155], off
	s_waitcnt lgkmcnt(7)
	v_mfma_f32_32x32x16_bf16 v[80:95], v[218:221], v[100:103], v[80:95]
	ds_read_b128 v[234:237], v143 offset:6816
	ds_read_b128 v[218:221], v168 offset:18016
	s_waitcnt lgkmcnt(7)
	v_mfma_f32_32x32x16_bf16 v[80:95], v[222:225], v[104:107], v[80:95]
	s_waitcnt lgkmcnt(5)
	v_mfma_f32_32x32x16_bf16 v[80:95], v[226:229], v[108:111], v[80:95]
	s_waitcnt lgkmcnt(3)
	v_mfma_f32_32x32x16_bf16 v[80:95], v[230:233], v[112:115], v[80:95]
	s_waitcnt lgkmcnt(1)
	v_mfma_f32_32x32x16_bf16 v[80:95], v[234:237], v[116:119], v[80:95]
	s_setprio 0

; #define MFMA32(a, b, c) __builtin_amdgcn_mfma_f32_32x32x16_bf16((a), (b), (c), 0, 0, 0)
; template <int DK, int DV>
; DI void attn_map(f32x16 (&O)[DV / 32], float& lsum, const u16* qrow, const u16* K1, int ldk1, const u16* K2, int ldk2, const u16* Vt, int nkeys, char* smem) {
;     ...
;     __builtin_amdgcn_s_setprio(1);
; #pragma unroll
;     for (int j = 0; j < 2; ++j) {
; #pragma unroll
;       for (int ks = 0; ks < DK / 16; ++ks) {
;         bf16x8 kf = *(const bf16x8*)(Ks + (j * 32 + r) * KST + ks * 16 + 8 * h);
;         s[j] = (ks == 0) ? MFMA32(kf, qf[ks], negm) : MFMA32(kf, qf[ks], s[j]);
;       }
;     }
;     {
;       constexpr int NQK = 2 * (DK / 16);
;       __builtin_amdgcn_sched_group_barrier(0x100, 2, 0);
; #pragma unroll
;       for (int q = 0; q < NQK - 2; ++q) { __builtin_amdgcn_sched_group_barrier(0x008, 1, 0); __builtin_amdgcn_sched_group_barrier(0x100, 1, 0); }
;       __builtin_amdgcn_sched_group_barrier(0x008, 2, 0);
;     }
.Lqk_last_C:
	s_setprio 1
	ds_read_b128 v[190:193], v143
	ds_read_b128 v[194:197], v143 offset:32
	ds_read_b128 v[198:201], v143 offset:64
	ds_read_b128 v[202:205], v143 offset:96
	s_waitcnt lgkmcnt(3)
	v_mfma_f32_32x32x16_bf16 v[64:79], v[190:193], v[96:99], v[16:31]
	ds_read_b128 v[206:209], v143 offset:128
	ds_read_b128 v[190:193], v168 offset:13312
	s_waitcnt lgkmcnt(4)
	v_mfma_f32_32x32x16_bf16 v[64:79], v[194:197], v[100:103], v[64:79]
	ds_read_b128 v[210:213], v143 offset:160
	ds_read_b128 v[194:197], v168 offset:17920
	s_waitcnt lgkmcnt(5)
	v_mfma_f32_32x32x16_bf16 v[64:79], v[198:201], v[104:107], v[64:79]
	ds_read_b128 v[214:217], v143 offset:6656
	ds_read_b128 v[198:201], v168 offset:13344
	s_waitcnt lgkmcnt(6)
	v_mfma_f32_32x32x16_bf16 v[64:79], v[202:205], v[108:111], v[64:79]
	ds_read_b128 v[218:221], v143 offset:6688
	ds_read_b128 v[202:205], v168 offset:17952
	s_waitcnt lgkmcnt(7)
	v_mfma_f32_32x32x16_bf16 v[64:79], v[206:209], v[112:115], v[64:79]
	ds_read_b128 v[222:225], v143 offset:6720
	ds_read_b128 v[206:209], v168 offset:13376
	s_waitcnt lgkmcnt(7)
	v_mfma_f32_32x32x16_bf16 v[64:79], v[210:213], v[116:119], v[64:79]
	ds_read_b128 v[226:229], v143 offset:6752
	ds_read_b128 v[210:213], v168 offset:17984
	s_waitcnt lgkmcnt(7)
	v_mfma_f32_32x32x16_bf16 v[80:95], v[214:217], v[96:99], v[16:31]
	ds_read_b128 v[230:233], v143 offset:6784
	ds_read_b128 v[214:217], v168 offset:13408
	s_waitcnt lgkmcnt(7)
	v_mfma_f32_32x32x16_bf16 v[80:95], v[218:221], v[100:103], v[80:95]
	ds_read_b128 v[234:237], v143 offset:6816
	ds_read_b128 v[218:221], v168 offset:18016
	s_waitcnt lgkmcnt(7)
	v_mfma_f32_32x32x16_bf16 v[80:95], v[222:225], v[104:107], v[80:95]
	s_waitcnt lgkmcnt(5)
	v_mfma_f32_32x32x16_bf16 v[80:95], v[226:229], v[108:111], v[80:95]
	s_waitcnt lgkmcnt(3)
	v_mfma_f32_32x32x16_bf16 v[80:95], v[230:233], v[112:115], v[80:95]
	s_waitcnt lgkmcnt(1)
	v_mfma_f32_32x32x16_bf16 v[80:95], v[234:237], v[116:119], v[80:95]
	s_setprio 0
	s_branch .Lqk_join_C

; #define MFMA32(a, b, c) __builtin_amdgcn_mfma_f32_32x32x16_bf16((a), (b), (c), 0, 0, 0)
; template <int DK, int DV>
; DI void attn_map(f32x16 (&O)[DV / 32], float& lsum, const u16* qrow, const u16* K1, int ldk1, const u16* K2, int ldk2, const u16* Vt, int nkeys, char* smem) {
;     ...
;     __syncthreads();
; #pragma unroll
;     for (int i = 0; i < NKR; ++i) { int id = tid + i * 256; int row = id / KCH, cc = id - row * KCH; *(u32x4*)(Ks + row * KST + cc * 8) = kreg[i]; }
; #pragma unroll
;     for (int i = 0; i < NVR; ++i) {
;       int id = tid + i * 256; int row = id >> 3, cc = id & 7;
;       u16* base = Vs + row * VST + (cc >> 1) * 16 + (cc & 1) * 4;
;       u32x2 t0 = {vreg[i].x, vreg[i].y}, t1 = {vreg[i].z, vreg[i].w};
;       *(u32x2*)base = t0; *(u32x2*)(base + 8) = t1;
;     }
;     __syncthreads();
;     if (k0 + 64 < nkeys) ATT_LOAD(k0 + 64)
;     f32x16 s[2];
;     __builtin_amdgcn_s_setprio(1);
; #pragma unroll
;     for (int j = 0; j < 2; ++j) {
; #pragma unroll
;       for (int ks = 0; ks < DK / 16; ++ks) {
;         bf16x8 kf = *(const bf16x8*)(Ks + (j * 32 + r) * KST + ks * 16 + 8 * h);
;         s[j] = (ks == 0) ? MFMA32(kf, qf[ks], negm) : MFMA32(kf, qf[ks], s[j]);
;       }
;     }
;     {
;       constexpr int NQK = 2 * (DK / 16);
;       __builtin_amdgcn_sched_group_barrier(0x100, 2, 0);
; #pragma unroll
;       for (int q = 0; q < NQK - 2; ++q) { __builtin_amdgcn_sched_group_barrier(0x008, 1, 0); __builtin_amdgcn_sched_group_barrier(0x100, 1, 0); }
;       __builtin_amdgcn_sched_group_barrier(0x008, 2, 0);
;     }
.LBB0_447:
	s_cmpk_gt_u32 s12, 0x10bf
	s_cselect_b64 s[8:9], -1, 0
	s_and_b64 vcc, exec, s[8:9]
	s_barrier
	s_waitcnt vmcnt(3)
	ds_write_b128 v139, v[112:115]
	s_waitcnt vmcnt(1)
	ds_write_b128 v140, v[116:119]
	ds_write2_b64 v141, v[120:121], v[122:123] offset0:128 offset1:130
	s_waitcnt vmcnt(0)
	ds_write2_b64 v142, v[124:125], v[126:127] offset0:128 offset1:130
	s_waitcnt lgkmcnt(0)
	s_barrier
	s_cbranch_vccnz .Lqk_last_D
	s_setprio 1
	ds_read_b128 v[200:203], v143
	ds_read_b128 v[204:207], v143 offset:32
	ds_read_b128 v[208:211], v143 offset:64
	ds_read_b128 v[212:215], v143 offset:96
	s_waitcnt lgkmcnt(3)
	v_mfma_f32_32x32x16_bf16 v[64:79], v[200:203], v[96:99], v[16:31]
	ds_read_b128 v[216:219], v143 offset:4608
	ds_read_b128 v[200:203], v143 offset:9216
	v_lshl_add_u64 v[236:237], v[136:137], 0, s[6:7]
	global_load_dwordx4 v[112:115], v[236:237], off
	s_waitcnt lgkmcnt(4)
	v_mfma_f32_32x32x16_bf16 v[64:79], v[204:207], v[100:103], v[64:79]
	ds_read_b128 v[220:223], v143 offset:4640
	ds_read_b128 v[204:207], v143 offset:13824
	v_lshl_add_u64 v[236:237], v[134:135], 0, s[6:7]
	global_load_dwordx4 v[116:119], v[236:237], off
	s_waitcnt lgkmcnt(5)
	v_mfma_f32_32x32x16_bf16 v[64:79], v[208:211], v[104:107], v[64:79]
	ds_read_b128 v[224:227], v143 offset:4672
	ds_read_b128 v[208:211], v143 offset:9248
	v_lshl_add_u64 v[236:237], v[132:133], 0, s[6:7]
	global_load_dwordx4 v[120:123], v[236:237], off
	s_waitcnt lgkmcnt(6)
	v_mfma_f32_32x32x16_bf16 v[64:79], v[212:215], v[108:111], v[64:79]
	ds_read_b128 v[228:231], v143 offset:4704
	ds_read_b128 v[212:215], v143 offset:13856
	v_lshl_add_u64 v[236:237], v[130:131], 0, s[6:7]
	global_load_dwordx4 v[124:127], v[236:237], off
	s_waitcnt lgkmcnt(7)
	v_mfma_f32_32x32x16_bf16 v[80:95], v[216:219], v[96:99], v[16:31]
	ds_read_b128 v[216:219], v143 offset:9280
	s_waitcnt lgkmcnt(6)
	v_mfma_f32_32x32x16_bf16 v[80:95], v[220:223], v[100:103], v[80:95]
	ds_read_b128 v[220:223], v143 offset:13888
	s_waitcnt lgkmcnt(5)
	v_mfma_f32_32x32x16_bf16 v[80:95], v[224:227], v[104:107], v[80:95]
	ds_read_b128 v[224:227], v143 offset:9312
	s_waitcnt lgkmcnt(4)
	v_mfma_f32_32x32x16_bf16 v[80:95], v[228:231], v[108:111], v[80:95]
	ds_read_b128 v[228:231], v143 offset:13920
	s_setprio 0

; #define MFMA32(a, b, c) __builtin_amdgcn_mfma_f32_32x32x16_bf16((a), (b), (c), 0, 0, 0)
; template <int DK, int DV>
; DI void attn_map(f32x16 (&O)[DV / 32], float& lsum, const u16* qrow, const u16* K1, int ldk1, const u16* K2, int ldk2, const u16* Vt, int nkeys, char* smem) {
;     ...
;     __builtin_amdgcn_s_setprio(1);
; #pragma unroll
;     for (int j = 0; j < 2; ++j) {
; #pragma unroll
;       for (int ks = 0; ks < DK / 16; ++ks) {
;         bf16x8 kf = *(const bf16x8*)(Ks + (j * 32 + r) * KST + ks * 16 + 8 * h);
;         s[j] = (ks == 0) ? MFMA32(kf, qf[ks], negm) : MFMA32(kf, qf[ks], s[j]);
;       }
;     }
;     {
;       constexpr int NQK = 2 * (DK / 16);
;       __builtin_amdgcn_sched_group_barrier(0x100, 2, 0);
; #pragma unroll
;       for (int q = 0; q < NQK - 2; ++q) { __builtin_amdgcn_sched_group_barrier(0x008, 1, 0); __builtin_amdgcn_sched_group_barrier(0x100, 1, 0); }
;       __builtin_amdgcn_sched_group_barrier(0x008, 2, 0);
;     }
.Lqk_last_D:
	s_setprio 1
	ds_read_b128 v[200:203], v143
	ds_read_b128 v[204:207], v143 offset:32
	ds_read_b128 v[208:211], v143 offset:64
	ds_read_b128 v[212:215], v143 offset:96
	s_waitcnt lgkmcnt(3)
	v_mfma_f32_32x32x16_bf16 v[64:79], v[200:203], v[96:99], v[16:31]
	ds_read_b128 v[216:219], v143 offset:4608
	ds_read_b128 v[200:203], v143 offset:9216
	s_waitcnt lgkmcnt(4)
	v_mfma_f32_32x32x16_bf16 v[64:79], v[204:207], v[100:103], v[64:79]
	ds_read_b128 v[220:223], v143 offset:4640
	ds_read_b128 v[204:207], v143 offset:13824
	s_waitcnt lgkmcnt(5)
	v_mfma_f32_32x32x16_bf16 v[64:79], v[208:211], v[104:107], v[64:79]
	ds_read_b128 v[224:227], v143 offset:4672
	ds_read_b128 v[208:211], v143 offset:9248
	s_waitcnt lgkmcnt(6)
	v_mfma_f32_32x32x16_bf16 v[64:79], v[212:215], v[108:111], v[64:79]
	ds_read_b128 v[228:231], v143 offset:4704
	ds_read_b128 v[212:215], v143 offset:13856
	s_waitcnt lgkmcnt(7)
	v_mfma_f32_32x32x16_bf16 v[80:95], v[216:219], v[96:99], v[16:31]
	ds_read_b128 v[216:219], v143 offset:9280
	s_waitcnt lgkmcnt(6)
	v_mfma_f32_32x32x16_bf16 v[80:95], v[220:223], v[100:103], v[80:95]
	ds_read_b128 v[220:223], v143 offset:13888
	s_waitcnt lgkmcnt(5)
	v_mfma_f32_32x32x16_bf16 v[80:95], v[224:227], v[104:107], v[80:95]
	ds_read_b128 v[224:227], v143 offset:9312
	s_waitcnt lgkmcnt(4)
	v_mfma_f32_32x32x16_bf16 v[80:95], v[228:231], v[108:111], v[80:95]
	ds_read_b128 v[228:231], v143 offset:13920
	s_setprio 0
	s_branch .Lqk_join_D
